# prep conv loop: weights loaded once per unit, all row loads of a loop trip issued together; XCD-local state units; P2/P4b epilogue load batching
# speedup vs baseline: 1.0213x; 1.0109x over previous
.LBB0_619:
	v_readlane_b32 s2, v254, 25
	s_ashr_i32 s2, s28, s2
	s_and_b32 s14, s2, 7
	v_readlane_b32 s2, v254, 26
	s_ashr_i32 s2, s28, s2
	s_ashr_i32 s3, s2, 31
	v_readlane_b32 s13, v254, 11
	v_mov_b32_e32 v27, v172
	s_lshl_b64 s[16:17], s[2:3], s13
	s_lshl_b32 s2, s2, 3
	s_or_b32 s2, s2, s14
	v_and_b32_e32 v0, 15, v27
	s_lshl_b32 s14, s14, 7
	v_lshl_or_b32 v1, v0, 3, s14
	s_ashr_i32 s3, s2, 31
	v_readlane_b32 s15, v254, 27
	v_lshlrev_b32_e32 v174, 2, v1
	s_lshl_b64 s[2:3], s[2:3], s15
	v_lshl_add_u64 v[24:25], s[0:1], 0, v[174:175]
	s_mov_b64 s[14:15], 0x2000
	v_lshl_add_u64 v[28:29], v[24:25], 0, s[14:15]
	s_mov_b64 s[14:15], 0x4000
	v_lshl_add_u64 v[30:31], v[24:25], 0, s[14:15]
	s_mov_b64 s[14:15], 0x1000
	v_lshl_add_u64 v[32:33], v[24:25], 0, s[14:15]
	s_mov_b64 s[14:15], 0x3000
	s_and_b32 s12, s28, s92
	v_lshl_add_u64 v[34:35], v[24:25], 0, s[14:15]
	s_mov_b64 s[14:15], 0x5000
	s_lshl_b32 s13, s12, 7
	v_lshl_add_u64 v[36:37], v[24:25], 0, s[14:15]
	s_lshl_b64 s[14:15], s[2:3], 1
	s_add_u32 s2, s20, s14
	s_addc_u32 s3, s21, s15
	v_lshlrev_b32_e32 v174, 9, v0
	v_lshl_add_u64 v[38:39], s[2:3], 0, v[174:175]
	s_add_u32 s2, s22, s14
	s_addc_u32 s3, s23, s15
	v_lshl_add_u64 v[40:41], s[2:3], 0, v[174:175]
	v_lshlrev_b32_e32 v174, 1, v1
	v_lshl_add_u32 v26, v0, 4, 0
	v_lshl_add_u64 v[42:43], s[10:11], 0, v[174:175]
	v_lshl_add_u64 v[44:45], s[6:7], 0, v[174:175]
	v_lshl_add_u64 v[46:47], s[8:9], 0, v[174:175]
	global_load_dwordx4 v[144:147], v[24:25], off
	global_load_dwordx4 v[148:151], v[24:25], off offset:16
	global_load_dwordx4 v[152:155], v[28:29], off
	global_load_dwordx4 v[156:159], v[28:29], off offset:16
	global_load_dwordx4 v[160:163], v[30:31], off
	global_load_dwordx4 v[164:167], v[30:31], off offset:16
	global_load_dwordx4 v[184:187], v[32:33], off
	global_load_dwordx4 v[188:191], v[32:33], off offset:16
	global_load_dwordx4 v[192:195], v[34:35], off
	global_load_dwordx4 v[196:199], v[34:35], off offset:16
	global_load_dwordx4 v[200:203], v[36:37], off
	global_load_dwordx4 v[204:207], v[36:37], off offset:16
	s_mov_b32 s29, 0
	s_branch .LBB0_621
.LBB0_620:
	s_or_b64 exec, exec, s[18:19]
	v_lshlrev_b32_e32 v22, 16, v8
	v_and_b32_e32 v23, 0xffff0000, v8
	v_lshlrev_b32_e32 v20, 16, v4
	v_and_b32_e32 v21, 0xffff0000, v4
	v_lshlrev_b32_e32 v66, 16, v0
	v_and_b32_e32 v67, 0xffff0000, v0
	v_lshlrev_b32_e32 v8, 16, v9
	v_and_b32_e32 v9, 0xffff0000, v9
	v_lshlrev_b32_e32 v4, 16, v5
	v_and_b32_e32 v5, 0xffff0000, v5
	s_addk_i32 s29, 0x400
	s_cmpk_eq_i32 s29, 0x800
	v_pk_mul_f32 v[22:23], v[192:193], v[22:23]
	s_nop 0
	v_pk_fma_f32 v[52:53], v[184:185], v[20:21], v[22:23]
	v_pk_mul_f32 v[8:9], v[194:195], v[8:9]
	v_pk_fma_f32 v[52:53], v[200:201], v[66:67], v[52:53]
	s_nop 0
	v_mul_f32_e32 v0, 0xbfb8aa3b, v52
	v_exp_f32_e32 v0, v0
	v_pk_fma_f32 v[4:5], v[186:187], v[4:5], v[8:9]
	v_lshlrev_b32_e32 v8, 16, v10
	v_and_b32_e32 v9, 0xffff0000, v10
	v_add_f32_e32 v0, 1.0, v0
	v_rcp_f32_e32 v58, v0
	v_mul_f32_e32 v0, 0xbfb8aa3b, v53
	v_exp_f32_e32 v0, v0
	v_pk_mul_f32 v[8:9], v[196:197], v[8:9]
	v_lshlrev_b32_e32 v54, 16, v2
	v_and_b32_e32 v55, 0xffff0000, v2
	v_add_f32_e32 v0, 1.0, v0
	v_rcp_f32_e32 v59, v0
	v_lshlrev_b32_e32 v0, 16, v1
	v_and_b32_e32 v1, 0xffff0000, v1
	v_pk_fma_f32 v[0:1], v[202:203], v[0:1], v[4:5]
	v_pk_mul_f32 v[52:53], v[52:53], v[58:59]
	v_mul_f32_e32 v4, 0xbfb8aa3b, v0
	v_mul_f32_e32 v5, 0xbfb8aa3b, v1
	v_exp_f32_e32 v4, v4
	v_exp_f32_e32 v5, v5
	v_pk_mul_f32 v[52:53], v[52:53], s[68:69] op_sel_hi:[1,0]
	v_add_f32_e32 v4, 1.0, v4
	v_add_f32_e32 v5, 1.0, v5
	v_rcp_f32_e32 v4, v4
	v_rcp_f32_e32 v5, v5
	s_nop 0
	v_pk_mul_f32 v[0:1], v[0:1], v[4:5]
	v_lshlrev_b32_e32 v4, 16, v6
	v_and_b32_e32 v5, 0xffff0000, v6
	v_pk_fma_f32 v[4:5], v[188:189], v[4:5], v[8:9]
	v_lshlrev_b32_e32 v6, 16, v7
	v_pk_fma_f32 v[4:5], v[204:205], v[54:55], v[4:5]
	v_and_b32_e32 v7, 0xffff0000, v7
	v_mul_f32_e32 v2, 0xbfb8aa3b, v4
	v_exp_f32_e32 v2, v2
	v_pk_mul_f32 v[0:1], v[0:1], s[68:69] op_sel_hi:[1,0]
	v_add_f32_e32 v2, 1.0, v2
	v_rcp_f32_e32 v8, v2
	v_mul_f32_e32 v2, 0xbfb8aa3b, v5
	v_exp_f32_e32 v2, v2
	s_nop 0
	v_add_f32_e32 v2, 1.0, v2
	v_rcp_f32_e32 v9, v2
	v_lshlrev_b32_e32 v2, 16, v3
	v_and_b32_e32 v3, 0xffff0000, v3
	v_pk_mul_f32 v[4:5], v[4:5], v[8:9]
	v_lshlrev_b32_e32 v8, 16, v11
	v_and_b32_e32 v9, 0xffff0000, v11
	v_pk_mul_f32 v[8:9], v[198:199], v[8:9]
	v_pk_mul_f32 v[4:5], v[4:5], s[68:69] op_sel_hi:[1,0]
	v_pk_fma_f32 v[6:7], v[190:191], v[6:7], v[8:9]
	v_cvt_pk_bf16_f32 v4, v4, v5
	v_pk_fma_f32 v[2:3], v[206:207], v[2:3], v[6:7]
	s_nop 0
	v_mul_f32_e32 v6, 0xbfb8aa3b, v2
	v_mul_f32_e32 v7, 0xbfb8aa3b, v3
	v_exp_f32_e32 v6, v6
	v_exp_f32_e32 v7, v7
	v_add_f32_e32 v6, 1.0, v6
	v_add_f32_e32 v7, 1.0, v7
	v_rcp_f32_e32 v6, v6
	v_rcp_f32_e32 v7, v7
	s_nop 0
	v_pk_mul_f32 v[2:3], v[2:3], v[6:7]
	s_nop 0
	v_pk_mul_f32 v[6:7], v[2:3], s[68:69] op_sel_hi:[1,0]
	v_cvt_pk_bf16_f32 v3, v0, v1
	v_lshl_add_u64 v[0:1], v[40:41], 0, v[50:51]
	v_cvt_pk_bf16_f32 v2, v52, v53
	v_cvt_pk_bf16_f32 v5, v6, v7
	v_lshl_add_u64 v[0:1], v[0:1], 0, v[174:175]
	global_store_dwordx4 v[0:1], v[2:5], off
	v_mad_u64_u32 v[0:1], s[2:3], v57, s67, v[26:27]
	ds_write2_b32 v0, v2, v3 offset1:1
	ds_write2_b32 v0, v4, v5 offset0:2 offset1:3
	v_mov_b64_e32 v[2:3], v[116:117]
	v_mov_b64_e32 v[4:5], v[118:119]
	v_add_u32_e32 v1, 0x8200, v0
	v_add_u32_e32 v0, 0x8208, v0
	ds_write2_b32 v1, v2, v3 offset1:1
	ds_write2_b32 v0, v4, v5 offset1:1
	s_cbranch_scc1 .LBB0_637

.LBB0_625:
	s_or_b64 exec, exec, s[18:19]
	v_lshl_add_u64 v[88:89], v[46:47], 0, v[48:49]
	global_load_dwordx4 v[76:79], v[88:89], off
	v_lshl_add_u64 v[90:91], v[42:43], 0, v[48:49]
	global_load_dwordx4 v[84:87], v[90:91], off
	s_and_saveexec_b64 s[18:19], s[2:3]
	s_cbranch_execz .Lp3e_a_1
	global_load_dwordx4 v[80:83], v[88:89], off offset:2048

.Lp3e_a_2:
	s_or_b64 exec, exec, s[18:19]
	v_add_u32_e32 v120, 0x200, v57
	v_ashrrev_i32_e32 v120, 4, v120
	v_add_u32_e32 v120, s13, v120
	v_ashrrev_i32_e32 v121, 31, v120
	v_cmp_lt_i32_e64 s[98:99], 0, v120
	v_cmp_gt_i32_e64 s[100:101], s71, v120
	v_lshl_add_u64 v[120:121], s[16:17], 0, v[120:121]
	v_lshlrev_b64 v[120:121], 11, v[120:121]
	v_lshl_add_u64 v[122:123], v[44:45], 0, v[120:121]
	v_lshl_add_u64 v[124:125], v[46:47], 0, v[120:121]
	v_lshl_add_u64 v[126:127], v[42:43], 0, v[120:121]
	global_load_dwordx4 v[96:99], v[122:123], off
	global_load_dwordx4 v[108:111], v[124:125], off
	global_load_dwordx4 v[116:119], v[126:127], off
	s_and_saveexec_b64 s[18:19], s[100:101]
	s_cbranch_execz .Lp3e_b_1
	global_load_dwordx4 v[100:103], v[122:123], off offset:2048
	global_load_dwordx4 v[112:115], v[124:125], off offset:2048
.Lp3e_b_1:
	s_or_b64 exec, exec, s[18:19]
	s_and_saveexec_b64 s[18:19], s[98:99]
	s_cbranch_execz .Lp3e_b_2
	global_load_dwordx4 v[92:95], v[122:123], off offset:-2048
	global_load_dwordx4 v[104:107], v[124:125], off offset:-2048
.Lp3e_b_2:
	s_or_b64 exec, exec, s[18:19]
	v_ashrrev_i32_e32 v12, 5, v174
	v_ashrrev_i32_e32 v13, 31, v12
	v_lshlrev_b64 v[50:51], 13, v[12:13]
	v_lshlrev_b32_e32 v12, 3, v58
	v_and_b32_e32 v59, 0xf8, v12
	s_waitcnt vmcnt(0)
	v_lshlrev_b32_e32 v22, 16, v8
	v_and_b32_e32 v23, 0xffff0000, v8
	v_lshlrev_b32_e32 v20, 16, v4
	v_and_b32_e32 v21, 0xffff0000, v4
	v_lshlrev_b32_e32 v54, 16, v0
	v_and_b32_e32 v55, 0xffff0000, v0
	v_lshlrev_b32_e32 v8, 16, v9
	v_and_b32_e32 v9, 0xffff0000, v9
	v_lshlrev_b32_e32 v4, 16, v5
	v_and_b32_e32 v5, 0xffff0000, v5
	v_lshlrev_b32_e32 v174, 1, v59
	v_pk_mul_f32 v[22:23], v[152:153], v[22:23]
	s_nop 0
	v_pk_fma_f32 v[60:61], v[144:145], v[20:21], v[22:23]
	v_pk_mul_f32 v[8:9], v[154:155], v[8:9]
	v_pk_fma_f32 v[54:55], v[160:161], v[54:55], v[60:61]
	s_nop 0
	v_mul_f32_e32 v0, 0xbfb8aa3b, v54
	v_exp_f32_e32 v0, v0
	v_pk_fma_f32 v[4:5], v[146:147], v[4:5], v[8:9]
	v_lshlrev_b32_e32 v8, 16, v10
	v_and_b32_e32 v9, 0xffff0000, v10
	v_add_f32_e32 v0, 1.0, v0
	v_rcp_f32_e32 v60, v0
	v_mul_f32_e32 v0, 0xbfb8aa3b, v55
	v_exp_f32_e32 v0, v0
	v_pk_mul_f32 v[8:9], v[156:157], v[8:9]
	v_add_f32_e32 v0, 1.0, v0
	v_rcp_f32_e32 v61, v0
	v_lshlrev_b32_e32 v0, 16, v1
	v_and_b32_e32 v1, 0xffff0000, v1
	v_pk_fma_f32 v[0:1], v[162:163], v[0:1], v[4:5]
	v_pk_mul_f32 v[54:55], v[54:55], v[60:61]
	v_mul_f32_e32 v4, 0xbfb8aa3b, v0
	v_mul_f32_e32 v5, 0xbfb8aa3b, v1
	v_exp_f32_e32 v4, v4
	v_exp_f32_e32 v5, v5
	v_lshlrev_b32_e32 v60, 16, v2
	v_and_b32_e32 v61, 0xffff0000, v2
	v_add_f32_e32 v4, 1.0, v4
	v_add_f32_e32 v5, 1.0, v5
	v_rcp_f32_e32 v4, v4
	v_rcp_f32_e32 v5, v5
	s_nop 0
	v_pk_mul_f32 v[4:5], v[0:1], v[4:5]
	v_lshlrev_b32_e32 v0, 16, v6
	v_and_b32_e32 v1, 0xffff0000, v6
	v_pk_fma_f32 v[0:1], v[148:149], v[0:1], v[8:9]
	v_lshlrev_b32_e32 v6, 16, v11
	v_pk_fma_f32 v[0:1], v[164:165], v[60:61], v[0:1]
	s_nop 0
	v_mul_f32_e32 v2, 0xbfb8aa3b, v0
	v_exp_f32_e32 v2, v2
	s_nop 0
	v_add_f32_e32 v2, 1.0, v2
	v_rcp_f32_e32 v8, v2
	v_mul_f32_e32 v2, 0xbfb8aa3b, v1
	v_exp_f32_e32 v2, v2
	s_nop 0
	v_add_f32_e32 v2, 1.0, v2
	v_rcp_f32_e32 v9, v2
	v_lshlrev_b32_e32 v2, 16, v3
	v_and_b32_e32 v3, 0xffff0000, v3
	v_pk_mul_f32 v[8:9], v[0:1], v[8:9]
	v_lshlrev_b32_e32 v0, 16, v7
	v_and_b32_e32 v1, 0xffff0000, v7
	v_and_b32_e32 v7, 0xffff0000, v11
	v_pk_mul_f32 v[6:7], v[158:159], v[6:7]
	s_nop 0
	v_pk_fma_f32 v[0:1], v[150:151], v[0:1], v[6:7]
	s_nop 0
	v_pk_fma_f32 v[0:1], v[166:167], v[2:3], v[0:1]
	s_nop 0
	v_mul_f32_e32 v2, 0xbfb8aa3b, v0
	v_mul_f32_e32 v3, 0xbfb8aa3b, v1
	v_exp_f32_e32 v2, v2
	v_exp_f32_e32 v3, v3
	v_add_f32_e32 v2, 1.0, v2
	v_add_f32_e32 v3, 1.0, v3
	v_rcp_f32_e32 v2, v2
	v_rcp_f32_e32 v3, v3
	s_nop 0
	v_pk_mul_f32 v[6:7], v[0:1], v[2:3]
	v_cvt_pk_bf16_f32 v1, v4, v5
	v_lshl_add_u64 v[4:5], v[38:39], 0, v[50:51]
	v_cvt_pk_bf16_f32 v0, v54, v55
	v_cvt_pk_bf16_f32 v2, v8, v9
	v_cvt_pk_bf16_f32 v3, v6, v7
	v_lshl_add_u64 v[4:5], v[4:5], 0, v[174:175]
	global_store_dwordx4 v[4:5], v[0:3], off
	v_mov_b32_e32 v4, 0
	v_mov_b32_e32 v5, 0
	v_mov_b32_e32 v0, 0
	v_mov_b32_e32 v6, 0
	v_mov_b32_e32 v7, 0
	s_and_saveexec_b64 s[18:19], vcc
	s_cbranch_execz .LBB0_627
	v_mov_b64_e32 v[4:5], v[72:73]
	v_mov_b64_e32 v[6:7], v[74:75]

.LBB0_629:
	s_or_b64 exec, exec, s[18:19]
	v_lshlrev_b32_e32 v22, 16, v8
	v_and_b32_e32 v23, 0xffff0000, v8
	v_lshlrev_b32_e32 v20, 16, v4
	v_and_b32_e32 v21, 0xffff0000, v4
	v_lshlrev_b32_e32 v68, 16, v0
	v_and_b32_e32 v69, 0xffff0000, v0
	v_lshlrev_b32_e32 v8, 16, v9
	v_and_b32_e32 v9, 0xffff0000, v9
	v_lshlrev_b32_e32 v4, 16, v5
	v_and_b32_e32 v5, 0xffff0000, v5
	v_pk_mul_f32 v[22:23], v[192:193], v[22:23]
	s_nop 0
	v_pk_fma_f32 v[52:53], v[184:185], v[20:21], v[22:23]
	v_pk_mul_f32 v[8:9], v[194:195], v[8:9]
	v_pk_fma_f32 v[52:53], v[200:201], v[68:69], v[52:53]
	s_nop 0
	v_mul_f32_e32 v0, 0xbfb8aa3b, v52
	v_exp_f32_e32 v0, v0
	v_pk_fma_f32 v[4:5], v[186:187], v[4:5], v[8:9]
	v_lshlrev_b32_e32 v8, 16, v10
	v_and_b32_e32 v9, 0xffff0000, v10
	v_add_f32_e32 v0, 1.0, v0
	v_rcp_f32_e32 v60, v0
	v_mul_f32_e32 v0, 0xbfb8aa3b, v53
	v_exp_f32_e32 v0, v0
	v_pk_mul_f32 v[8:9], v[196:197], v[8:9]
	v_lshlrev_b32_e32 v54, 16, v2
	v_and_b32_e32 v55, 0xffff0000, v2
	v_add_f32_e32 v0, 1.0, v0
	v_rcp_f32_e32 v61, v0
	v_lshlrev_b32_e32 v0, 16, v1
	v_and_b32_e32 v1, 0xffff0000, v1
	v_pk_fma_f32 v[0:1], v[202:203], v[0:1], v[4:5]
	v_pk_mul_f32 v[52:53], v[52:53], v[60:61]
	v_mul_f32_e32 v4, 0xbfb8aa3b, v0
	v_mul_f32_e32 v5, 0xbfb8aa3b, v1
	v_exp_f32_e32 v4, v4
	v_exp_f32_e32 v5, v5
	v_pk_mul_f32 v[52:53], v[52:53], s[68:69] op_sel_hi:[1,0]
	v_add_f32_e32 v4, 1.0, v4
	v_add_f32_e32 v5, 1.0, v5
	v_rcp_f32_e32 v4, v4
	v_rcp_f32_e32 v5, v5
	s_nop 0
	v_pk_mul_f32 v[0:1], v[0:1], v[4:5]
	v_lshlrev_b32_e32 v4, 16, v6
	v_and_b32_e32 v5, 0xffff0000, v6
	v_pk_fma_f32 v[4:5], v[188:189], v[4:5], v[8:9]
	v_lshlrev_b32_e32 v6, 16, v7
	v_pk_fma_f32 v[4:5], v[204:205], v[54:55], v[4:5]
	v_and_b32_e32 v7, 0xffff0000, v7
	v_mul_f32_e32 v2, 0xbfb8aa3b, v4
	v_exp_f32_e32 v2, v2
	v_pk_mul_f32 v[0:1], v[0:1], s[68:69] op_sel_hi:[1,0]
	v_add_f32_e32 v2, 1.0, v2
	v_rcp_f32_e32 v8, v2
	v_mul_f32_e32 v2, 0xbfb8aa3b, v5
	v_exp_f32_e32 v2, v2
	s_nop 0
	v_add_f32_e32 v2, 1.0, v2
	v_rcp_f32_e32 v9, v2
	v_lshlrev_b32_e32 v2, 16, v3
	v_and_b32_e32 v3, 0xffff0000, v3
	v_pk_mul_f32 v[4:5], v[4:5], v[8:9]
	v_lshlrev_b32_e32 v8, 16, v11
	v_and_b32_e32 v9, 0xffff0000, v11
	v_pk_mul_f32 v[8:9], v[198:199], v[8:9]
	v_pk_mul_f32 v[4:5], v[4:5], s[68:69] op_sel_hi:[1,0]
	v_pk_fma_f32 v[6:7], v[190:191], v[6:7], v[8:9]
	v_cvt_pk_bf16_f32 v4, v4, v5
	v_pk_fma_f32 v[2:3], v[206:207], v[2:3], v[6:7]
	s_nop 0
	v_mul_f32_e32 v6, 0xbfb8aa3b, v2
	v_mul_f32_e32 v7, 0xbfb8aa3b, v3
	v_exp_f32_e32 v6, v6
	v_exp_f32_e32 v7, v7
	v_add_f32_e32 v6, 1.0, v6
	v_add_f32_e32 v7, 1.0, v7
	v_rcp_f32_e32 v6, v6
	v_rcp_f32_e32 v7, v7
	s_nop 0
	v_pk_mul_f32 v[2:3], v[2:3], v[6:7]
	s_nop 0
	v_pk_mul_f32 v[6:7], v[2:3], s[68:69] op_sel_hi:[1,0]
	v_cvt_pk_bf16_f32 v3, v0, v1
	v_lshl_add_u64 v[0:1], v[40:41], 0, v[50:51]
	v_cvt_pk_bf16_f32 v2, v52, v53
	v_cvt_pk_bf16_f32 v5, v6, v7
	v_lshl_add_u64 v[0:1], v[0:1], 0, v[174:175]
	global_store_dwordx4 v[0:1], v[2:5], off
	v_mad_u64_u32 v[0:1], s[2:3], v58, s67, v[26:27]
	ds_write2_b32 v0, v2, v3 offset1:1
	ds_write2_b32 v0, v4, v5 offset0:2 offset1:3
	v_mov_b64_e32 v[2:3], v[84:85]
	v_mov_b64_e32 v[4:5], v[86:87]
	v_add_u32_e32 v1, 0x8200, v0
	v_add_u32_e32 v0, 0x8208, v0
	v_mov_b32_e32 v6, 0
	v_mov_b32_e32 v7, 0
	ds_write2_b32 v0, v4, v5 offset1:1
	v_add_u32_e32 v0, 0x200, v57
	v_ashrrev_i32_e32 v57, 4, v0
	v_add_u32_e32 v174, s13, v57
	ds_write2_b32 v1, v2, v3 offset1:1
	v_lshl_add_u64 v[2:3], s[16:17], 0, v[174:175]
	v_mov_b32_e32 v0, 0
	v_cmp_lt_i32_e32 vcc, 0, v174
	v_lshlrev_b64 v[52:53], 11, v[2:3]
	v_mov_b32_e32 v4, 0
	v_mov_b32_e32 v5, 0
	s_and_saveexec_b64 s[2:3], vcc
	s_cbranch_execz .LBB0_631
	v_mov_b64_e32 v[4:5], v[92:93]
	v_mov_b64_e32 v[6:7], v[94:95]
.LBB0_631:
	s_or_b64 exec, exec, s[2:3]
	v_ashrrev_i32_e32 v3, 31, v174
	v_mov_b32_e32 v2, v174
	v_lshl_add_u64 v[2:3], s[16:17], 0, v[2:3]
	v_lshlrev_b64 v[48:49], 11, v[2:3]
	v_mov_b64_e32 v[8:9], v[96:97]
	v_mov_b64_e32 v[10:11], v[98:99]
	v_cmp_gt_i32_e64 s[2:3], s71, v174
	v_mov_b32_e32 v1, 0
	v_mov_b32_e32 v2, 0
	v_mov_b32_e32 v3, 0
	s_and_saveexec_b64 s[18:19], s[2:3]
	s_cbranch_execz .LBB0_633
	v_mov_b64_e32 v[0:1], v[100:101]
	v_mov_b64_e32 v[2:3], v[102:103]
.LBB0_633:
	s_or_b64 exec, exec, s[18:19]
	v_ashrrev_i32_e32 v12, 5, v174
	v_ashrrev_i32_e32 v13, 31, v12
	v_lshlrev_b64 v[50:51], 13, v[12:13]
	v_lshlrev_b32_e32 v12, 3, v57
	v_and_b32_e32 v70, 0xf8, v12
	v_lshlrev_b32_e32 v22, 16, v8
	v_and_b32_e32 v23, 0xffff0000, v8
	v_lshlrev_b32_e32 v20, 16, v4
	v_and_b32_e32 v21, 0xffff0000, v4
	v_lshlrev_b32_e32 v54, 16, v0
	v_and_b32_e32 v55, 0xffff0000, v0
	v_lshlrev_b32_e32 v8, 16, v9
	v_and_b32_e32 v9, 0xffff0000, v9
	v_lshlrev_b32_e32 v4, 16, v5
	v_and_b32_e32 v5, 0xffff0000, v5
	v_lshlrev_b32_e32 v174, 1, v70
	v_pk_mul_f32 v[22:23], v[152:153], v[22:23]
	s_nop 0
	v_pk_fma_f32 v[58:59], v[144:145], v[20:21], v[22:23]
	v_pk_mul_f32 v[8:9], v[154:155], v[8:9]
	v_pk_fma_f32 v[54:55], v[160:161], v[54:55], v[58:59]
	s_nop 0
	v_mul_f32_e32 v0, 0xbfb8aa3b, v54
	v_exp_f32_e32 v0, v0
	v_pk_fma_f32 v[4:5], v[146:147], v[4:5], v[8:9]
	v_lshlrev_b32_e32 v8, 16, v10
	v_and_b32_e32 v9, 0xffff0000, v10
	v_add_f32_e32 v0, 1.0, v0
	v_rcp_f32_e32 v58, v0
	v_mul_f32_e32 v0, 0xbfb8aa3b, v55
	v_exp_f32_e32 v0, v0
	v_pk_mul_f32 v[8:9], v[156:157], v[8:9]
	v_add_f32_e32 v0, 1.0, v0
	v_rcp_f32_e32 v59, v0
	v_lshlrev_b32_e32 v0, 16, v1
	v_and_b32_e32 v1, 0xffff0000, v1
	v_pk_fma_f32 v[0:1], v[162:163], v[0:1], v[4:5]
	v_pk_mul_f32 v[54:55], v[54:55], v[58:59]
	v_mul_f32_e32 v4, 0xbfb8aa3b, v0
	v_mul_f32_e32 v5, 0xbfb8aa3b, v1
	v_exp_f32_e32 v4, v4
	v_exp_f32_e32 v5, v5
	v_lshlrev_b32_e32 v58, 16, v2
	v_and_b32_e32 v59, 0xffff0000, v2
	v_add_f32_e32 v4, 1.0, v4
	v_add_f32_e32 v5, 1.0, v5
	v_rcp_f32_e32 v4, v4
	v_rcp_f32_e32 v5, v5
	s_nop 0
	v_pk_mul_f32 v[4:5], v[0:1], v[4:5]
	v_lshlrev_b32_e32 v0, 16, v6
	v_and_b32_e32 v1, 0xffff0000, v6
	v_pk_fma_f32 v[0:1], v[148:149], v[0:1], v[8:9]
	v_lshlrev_b32_e32 v6, 16, v11
	v_pk_fma_f32 v[0:1], v[164:165], v[58:59], v[0:1]
	s_nop 0
	v_mul_f32_e32 v2, 0xbfb8aa3b, v0
	v_exp_f32_e32 v2, v2
	s_nop 0
	v_add_f32_e32 v2, 1.0, v2
	v_rcp_f32_e32 v8, v2
	v_mul_f32_e32 v2, 0xbfb8aa3b, v1
	v_exp_f32_e32 v2, v2
	s_nop 0
	v_add_f32_e32 v2, 1.0, v2
	v_rcp_f32_e32 v9, v2
	v_lshlrev_b32_e32 v2, 16, v3
	v_and_b32_e32 v3, 0xffff0000, v3
	v_pk_mul_f32 v[8:9], v[0:1], v[8:9]
	v_lshlrev_b32_e32 v0, 16, v7
	v_and_b32_e32 v1, 0xffff0000, v7
	v_and_b32_e32 v7, 0xffff0000, v11
	v_pk_mul_f32 v[6:7], v[158:159], v[6:7]
	s_nop 0
	v_pk_fma_f32 v[0:1], v[150:151], v[0:1], v[6:7]
	s_nop 0
	v_pk_fma_f32 v[0:1], v[166:167], v[2:3], v[0:1]
	s_nop 0
	v_mul_f32_e32 v2, 0xbfb8aa3b, v0
	v_mul_f32_e32 v3, 0xbfb8aa3b, v1
	v_exp_f32_e32 v2, v2
	v_exp_f32_e32 v3, v3
	v_add_f32_e32 v2, 1.0, v2
	v_add_f32_e32 v3, 1.0, v3
	v_rcp_f32_e32 v2, v2
	v_rcp_f32_e32 v3, v3
	s_nop 0
	v_pk_mul_f32 v[6:7], v[0:1], v[2:3]
	v_cvt_pk_bf16_f32 v1, v4, v5
	v_lshl_add_u64 v[4:5], v[38:39], 0, v[50:51]
	v_cvt_pk_bf16_f32 v0, v54, v55
	v_cvt_pk_bf16_f32 v2, v8, v9
	v_cvt_pk_bf16_f32 v3, v6, v7
	v_lshl_add_u64 v[4:5], v[4:5], 0, v[174:175]
	global_store_dwordx4 v[4:5], v[0:3], off
	v_mov_b32_e32 v4, 0
	v_mov_b32_e32 v5, 0
	v_mov_b32_e32 v0, 0
	v_mov_b32_e32 v6, 0
	v_mov_b32_e32 v7, 0
	s_and_saveexec_b64 s[18:19], vcc
	s_cbranch_execz .LBB0_635
	v_mov_b64_e32 v[4:5], v[104:105]
	v_mov_b64_e32 v[6:7], v[106:107]
.LBB0_635:
	s_or_b64 exec, exec, s[18:19]
	v_mov_b64_e32 v[8:9], v[108:109]
	v_mov_b64_e32 v[10:11], v[110:111]
	v_mov_b32_e32 v1, 0
	v_mov_b32_e32 v2, 0
	v_mov_b32_e32 v3, 0
	s_and_saveexec_b64 s[18:19], s[2:3]
	s_cbranch_execz .LBB0_620
	v_mov_b64_e32 v[0:1], v[112:113]
	v_mov_b64_e32 v[2:3], v[114:115]
	s_branch .LBB0_620
